# speedup vs baseline: 1.0069x; 1.0069x over previous
; #define MFMA4(a, b, c) __builtin_amdgcn_mfma_f32_16x16x16bf16_1k(a, b, c, 0, 0, 0)
; __device__ __forceinline__ void scan_pc(const Params& p, int j, const u16* R, const u16* K, const u16* V, u16* Y, u16* YB) {
;     ...
;       u16* IMG = shm + (c % 3) * IMG_ELEMS;
;       u16* MM = shm + 4 * IMG_ELEMS + (c & 1) * MM_ELEMS;
;       int ai = (w4 < 2) ? 0 : 1, bi = (w4 & 1) ? 3 : 2;
;       f32x4 mt = {0.f, 0.f, 0.f, 0.f}, nc = {0.f, 0.f, 0.f, 0.f};
;       _Pragma("unroll") for (int kb = 0; kb < 4; ++kb) {
;         s4 xa = *reinterpret_cast<const s4*>(IMG + (ai * 16 + fr) * XT_LD + kb * 16 + fq * 4);
;         s4 xb = *reinterpret_cast<const s4*>(IMG + (bi * 16 + fr) * XT_LD + kb * 16 + fq * 4);
;         mt = MFMA4(xb, xa, mt);
;         if (w4 == 0) nc = MFMA4(xa, xb, nc);
;       }
;       float* SSQ = reinterpret_cast<float*>(IMG + IMG_PL) + 128;
;       float inv_t = rsqrtf(fmaxf((SSQ[fr] + SSQ[16 + fr]) + (SSQ[32 + fr] + SSQ[48 + fr]), 1e-24f));
;       if (w4 == 3) SSQ[64 + fr] = inv_t;
;       float ivr = (w4 < 2) ? inv_t : 1.f;
;       float sc_[4];
;       _Pragma("unroll") for (int jj = 0; jj < 4; ++jj) {
;         float ivj = __builtin_bit_cast(float, __builtin_amdgcn_ds_bpermute(((lane & 48) | (fq * 4 + jj)) << 2, __builtin_bit_cast(int, inv_t)));
;         sc_[jj] = ivr * (((w4 & 1) == 0) ? ivj : 1.f);
;         mt[jj] *= sc_[jj] * keepm[jj];
;       }
;       if (w4 == 0) {
;         _Pragma("unroll") for (int jj = 0; jj < 4; ++jj) nc[jj] *= sc_[jj] * keepn[jj];
;         f32x4 z4 = {0.f, 0.f, 0.f, 0.f};
;         s4 pN = pack4v(nc), pNT = pack4v(mt);
;         f32x4 n2 = MFMA4(pNT, pN, z4);
;         f32x4 n2t = MFMA4(pN, pNT, z4);
;         s4 pN2 = pack4v(n2), pN2T = pack4v(n2t);
;         f32x4 n4 = MFMA4(pN2T, pN2, z4);
;         f32x4 n4t = MFMA4(pN2, pN2T, z4);
;         s4 pN4 = pack4v(n4), pN4T = pack4v(n4t);
;         f32x4 n8 = MFMA4(pN4T, pN4, z4);
;         s4 pN8 = pack4v(n8);
;         f32x4 tt = mt;
;         _Pragma("unroll") for (int jj = 0; jj < 4; ++jj) tt[jj] += diagm[jj];
;         tt = MFMA4(pN2, pack4v(tt), tt);
;         tt = MFMA4(pN4, pack4v(tt), tt);
;         tt = MFMA4(pN8, pack4v(tt), tt);
;         mt = tt;
;     ...
;       _Pragma("unroll") for (int jj = 0; jj < 4; ++jj)
;         sto<u16>(Yw, (unsigned)(offK0[jj] + c * dK), f2b(ymode == 1 ? y[jj] + yo[jj] : y[jj]));
.Lyold_done_a:
	s_nop 4
	v_add_f32_e32 v60, v87, v92
	v_cndmask_b32_e64 v92, v92, v60, s[20:21]
	v_add_f32_e32 v64, v86, v93
	v_mfma_f32_16x16x16_bf16 v[60:63], v[68:69], v[70:71], v[194:197]
	v_cvt_pk_bf16_f32 v68, v92, s0
	v_cndmask_b32_e64 v64, v93, v64, s[20:21]
	v_add_f32_e32 v65, v89, v94
	global_store_short v91, v68, s[70:71]
	v_add_u32_e32 v68, s74, v178
	v_cvt_pk_bf16_f32 v64, v64, s0
	v_cndmask_b32_e64 v65, v94, v65, s[20:21]
	global_store_short v68, v64, s[70:71]
	v_add_u32_e32 v64, s74, v177
	v_cvt_pk_bf16_f32 v65, v65, s0
	global_store_short v64, v65, s[70:71]
	v_add_f32_e32 v64, v88, v95
	s_waitcnt lgkmcnt(2)
	v_mfma_f32_16x16x16_bf16 v[32:35], v[198:199], v[70:71], v[32:35]
	v_cndmask_b32_e64 v64, v95, v64, s[20:21]
	v_add_u32_e32 v65, s74, v176
	v_cvt_pk_bf16_f32 v64, v64, s0
	v_mfma_f32_16x16x16_bf16 v[36:39], v[200:201], v[70:71], v[36:39]
	global_store_short v65, v64, s[70:71]
	v_add_u32_e32 v64, 1, v90
	v_cmp_gt_u32_e32 vcc, s2, v64
	s_and_saveexec_b64 s[62:63], vcc
	s_cbranch_execz .LBB0_2738
	v_add_u32_e32 v64, s75, v90
	v_mad_u32_u24 v91, v64, s80, 0
	v_add3_u32 v180, v91, v136, v179
	v_add3_u32 v181, v91, v134, v179
	ds_read2_b64 v[206:209], v180 offset1:4
	ds_read2_b64 v[210:213], v181 offset1:4
	ds_read2_b64 v[214:217], v180 offset0:8 offset1:12
	ds_read2_b64 v[92:95], v181 offset0:8 offset1:12
	v_lshl_add_u32 v218, v96, 2, v91
	v_add_u32_e32 v219, 0x4400, v218
	ds_read2_b32 v[220:221], v219 offset1:16
	ds_read2_b32 v[222:223], v219 offset0:32 offset1:48
	v_readlane_b32 s76, v247, 14
	v_readlane_b32 s77, v247, 15
	v_readlane_b32 s78, v247, 16
	v_readlane_b32 s79, v247, 17
	v_mov_b64_e32 v[68:69], s[76:77]
	s_waitcnt lgkmcnt(4)
	v_mfma_f32_16x16x32_bf16 v[64:67], v[206:209], v[210:213], 0
	v_mov_b64_e32 v[70:71], s[78:79]
	s_and_saveexec_b64 s[30:31], s[14:15]
	v_mfma_f32_16x16x32_bf16 v[68:71], v[210:213], v[206:209], 0
	s_or_b64 exec, exec, s[30:31]
	s_waitcnt lgkmcnt(2)
	v_mfma_f32_16x16x32_bf16 v[64:67], v[214:217], v[92:95], v[64:67]
	s_and_saveexec_b64 s[30:31], s[14:15]
	v_mfma_f32_16x16x32_bf16 v[68:71], v[92:95], v[214:217], v[68:71]
	s_or_b64 exec, exec, s[30:31]
	v_lshl_add_u32 v93, v96, 2, v91
	s_waitcnt lgkmcnt(0)
	v_add_f32_e32 v180, v220, v221
	v_add_f32_e32 v92, v222, v223
	v_add_f32_e32 v92, v180, v92
	v_max_f32_e32 v92, 0x179abe15, v92
	v_rsq_f32_e32 v92, v92
	s_and_saveexec_b64 s[30:31], s[16:17]
	ds_write_b32 v93, v92 offset:17664
	s_or_b64 exec, exec, s[30:31]
	ds_bpermute_b32 v93, v138, v92
	ds_bpermute_b32 v94, v139, v92
	v_cndmask_b32_e64 v95, 1.0, v92, s[6:7]
	ds_bpermute_b32 v180, v140, v92
	ds_bpermute_b32 v224, v141, v92
	s_waitcnt lgkmcnt(3)
	v_cndmask_b32_e64 v93, 1.0, v93, s[18:19]
	s_waitcnt lgkmcnt(2)
	v_cndmask_b32_e64 v94, 1.0, v94, s[18:19]
	v_mul_f32_e32 v93, v95, v93
	v_mul_f32_e32 v181, v98, v93
	v_mul_f32_e32 v94, v95, v94
	v_mul_f32_e32 v64, v64, v181
	v_mul_f32_e32 v181, v101, v94
	v_mul_f32_e32 v65, v65, v181
	s_waitcnt lgkmcnt(1)
	v_cndmask_b32_e64 v92, 1.0, v180, s[18:19]
	v_mul_f32_e32 v92, v95, v92
	v_mul_f32_e32 v180, v104, v92
	v_mul_f32_e32 v66, v66, v180
	s_waitcnt lgkmcnt(0)
	v_cndmask_b32_e64 v180, 1.0, v224, s[18:19]
	v_mul_f32_e32 v95, v95, v180
	v_mul_f32_e32 v180, v107, v95
	v_mul_f32_e32 v67, v67, v180
	s_and_saveexec_b64 s[30:31], s[14:15]
	s_cbranch_execz .LBB0_2734
	v_mul_f32_e32 v93, v99, v93
	v_mul_f32_e32 v92, v105, v92
	v_mul_f32_e32 v68, v68, v93
	v_mul_f32_e32 v93, v102, v94
	v_mul_f32_e32 v70, v70, v92
	v_mul_f32_e32 v92, v108, v95
	v_mul_f32_e32 v69, v69, v93
	v_mul_f32_e32 v71, v71, v92
	v_cvt_pk_bf16_f32 v92, v68, v69
	v_cvt_pk_bf16_f32 v93, v70, v71
	v_cvt_pk_bf16_f32 v94, v64, v65
	v_cvt_pk_bf16_f32 v95, v66, v67
	v_add_f32_e32 v64, v100, v64
	v_add_f32_e32 v65, v103, v65
	v_mfma_f32_16x16x16_bf16 v[68:71], v[94:95], v[92:93], 0
	v_add_f32_e32 v66, v106, v66
	v_add_f32_e32 v67, v109, v67
	v_mfma_f32_16x16x16_bf16 v[92:95], v[92:93], v[94:95], 0
	s_nop 4
	v_cvt_pk_bf16_f32 v180, v68, v69
	v_cvt_pk_bf16_f32 v181, v70, v71
	s_nop 0
	v_cvt_pk_bf16_f32 v92, v92, v93
	v_cvt_pk_bf16_f32 v93, v94, v95
	s_nop 1
	v_mfma_f32_16x16x16_bf16 v[68:71], v[92:93], v[180:181], 0
	v_mfma_f32_16x16x16_bf16 v[92:95], v[180:181], v[92:93], 0
	s_nop 6
	v_cvt_pk_bf16_f32 v194, v68, v69
	v_cvt_pk_bf16_f32 v195, v70, v71
	v_cvt_pk_bf16_f32 v68, v92, v93
	v_cvt_pk_bf16_f32 v69, v94, v95
	s_nop 1
	v_mfma_f32_16x16x16_bf16 v[68:71], v[68:69], v[194:195], 0
	s_nop 7
	v_cvt_pk_bf16_f32 v68, v68, v69
	v_cvt_pk_bf16_f32 v69, v70, v71
	v_cvt_pk_bf16_f32 v70, v64, v65
	v_cvt_pk_bf16_f32 v71, v66, v67
	s_nop 1
	v_mfma_f32_16x16x16_bf16 v[64:67], v[180:181], v[70:71], v[64:67]
	s_nop 7
	v_cvt_pk_bf16_f32 v70, v64, v65
	v_cvt_pk_bf16_f32 v71, v66, v67
	s_nop 1
	v_mfma_f32_16x16x16_bf16 v[64:67], v[194:195], v[70:71], v[64:67]
	s_nop 7
	v_cvt_pk_bf16_f32 v70, v64, v65
	v_cvt_pk_bf16_f32 v71, v66, v67
	s_nop 1
	v_mfma_f32_16x16x16_bf16 v[64:67], v[68:69], v[70:71], v[64:67]

; #define MFMA4(a, b, c) __builtin_amdgcn_mfma_f32_16x16x16bf16_1k(a, b, c, 0, 0, 0)
; __device__ __forceinline__ void scan_pc(const Params& p, int j, const u16* R, const u16* K, const u16* V, u16* Y, u16* YB) {
;     ...
;       u16* IMG = shm + (c % 3) * IMG_ELEMS;
;       u16* MM = shm + 4 * IMG_ELEMS + (c & 1) * MM_ELEMS;
;       int ai = (w4 < 2) ? 0 : 1, bi = (w4 & 1) ? 3 : 2;
;       f32x4 mt = {0.f, 0.f, 0.f, 0.f}, nc = {0.f, 0.f, 0.f, 0.f};
;       _Pragma("unroll") for (int kb = 0; kb < 4; ++kb) {
;         s4 xa = *reinterpret_cast<const s4*>(IMG + (ai * 16 + fr) * XT_LD + kb * 16 + fq * 4);
;         s4 xb = *reinterpret_cast<const s4*>(IMG + (bi * 16 + fr) * XT_LD + kb * 16 + fq * 4);
;         mt = MFMA4(xb, xa, mt);
;         if (w4 == 0) nc = MFMA4(xa, xb, nc);
;       }
;       float* SSQ = reinterpret_cast<float*>(IMG + IMG_PL) + 128;
;       float inv_t = rsqrtf(fmaxf((SSQ[fr] + SSQ[16 + fr]) + (SSQ[32 + fr] + SSQ[48 + fr]), 1e-24f));
;       if (w4 == 3) SSQ[64 + fr] = inv_t;
;       float ivr = (w4 < 2) ? inv_t : 1.f;
;       float sc_[4];
;       _Pragma("unroll") for (int jj = 0; jj < 4; ++jj) {
;         float ivj = __builtin_bit_cast(float, __builtin_amdgcn_ds_bpermute(((lane & 48) | (fq * 4 + jj)) << 2, __builtin_bit_cast(int, inv_t)));
;         sc_[jj] = ivr * (((w4 & 1) == 0) ? ivj : 1.f);
;         mt[jj] *= sc_[jj] * keepm[jj];
;       }
;       if (w4 == 0) {
;         _Pragma("unroll") for (int jj = 0; jj < 4; ++jj) nc[jj] *= sc_[jj] * keepn[jj];
;         f32x4 z4 = {0.f, 0.f, 0.f, 0.f};
;         s4 pN = pack4v(nc), pNT = pack4v(mt);
;         f32x4 n2 = MFMA4(pNT, pN, z4);
;         f32x4 n2t = MFMA4(pN, pNT, z4);
;         s4 pN2 = pack4v(n2), pN2T = pack4v(n2t);
;         f32x4 n4 = MFMA4(pN2T, pN2, z4);
;         f32x4 n4t = MFMA4(pN2, pN2T, z4);
;         s4 pN4 = pack4v(n4), pN4T = pack4v(n4t);
;         f32x4 n8 = MFMA4(pN4T, pN4, z4);
;         s4 pN8 = pack4v(n8);
;         f32x4 tt = mt;
;         _Pragma("unroll") for (int jj = 0; jj < 4; ++jj) tt[jj] += diagm[jj];
;         tt = MFMA4(pN2, pack4v(tt), tt);
;         tt = MFMA4(pN4, pack4v(tt), tt);
;         tt = MFMA4(pN8, pack4v(tt), tt);
;         mt = tt;
;     ...
;       _Pragma("unroll") for (int jj = 0; jj < 4; ++jj)
;         sto<u16>(Yw, (unsigned)(offK0[jj] + c * dK), f2b(ymode == 1 ? y[jj] + yo[jj] : y[jj]));
.Lyold_done_b:
	s_nop 1
	v_add_u32_e32 v94, 2, v90
	s_nop 3
	v_add_f32_e32 v92, v87, v66
	v_cndmask_b32_e64 v66, v66, v92, s[20:21]
	v_add_f32_e32 v65, v86, v67
	v_cvt_pk_bf16_f32 v64, v66, s0
	v_cndmask_b32_e64 v65, v67, v65, s[20:21]
	s_waitcnt lgkmcnt(3)
	v_mfma_f32_16x16x16_bf16 v[32:35], v[194:195], v[202:203], v[32:35]
	global_store_short v91, v64, s[70:71]
	v_add_u32_e32 v64, s74, v173
	v_cvt_pk_bf16_f32 v65, v65, s0
	v_mfma_f32_16x16x16_bf16 v[36:39], v[196:197], v[202:203], v[36:39]
	global_store_short v64, v65, s[70:71]
	v_add_f32_e32 v65, v89, v68
	v_cndmask_b32_e64 v65, v68, v65, s[20:21]
	v_mfma_f32_16x16x16_bf16 v[44:47], v[70:71], v[180:181], v[44:47]
	v_add_u32_e32 v64, s74, v172
	v_cvt_pk_bf16_f32 v65, v65, s0
	global_store_short v64, v65, s[70:71]
	s_waitcnt lgkmcnt(2)
	v_mfma_f32_16x16x16_bf16 v[32:35], v[198:199], v[180:181], v[32:35]
	v_add_f32_e32 v64, v88, v69
	v_cndmask_b32_e64 v64, v69, v64, s[20:21]
	v_add_u32_e32 v65, s74, v171
	v_mfma_f32_16x16x16_bf16 v[36:39], v[200:201], v[180:181], v[36:39]
	v_cvt_pk_bf16_f32 v64, v64, s0
	v_cmp_gt_u32_e32 vcc, s2, v94
	global_store_short v65, v64, s[70:71]
	s_and_saveexec_b64 s[62:63], vcc
	s_cbranch_execz .LBB0_2763
	v_add_u32_e32 v64, s76, v90
	v_mad_u32_u24 v95, v64, s80, 0
	v_add3_u32 v180, v95, v136, v179
	v_add3_u32 v179, v95, v134, v179
	ds_read2_b64 v[206:209], v180 offset1:4
	ds_read2_b64 v[210:213], v179 offset1:4
	ds_read2_b64 v[214:217], v180 offset0:8 offset1:12
	ds_read2_b64 v[90:93], v179 offset0:8 offset1:12
	v_lshl_add_u32 v218, v96, 2, v95
	v_add_u32_e32 v219, 0x4400, v218
	ds_read2_b32 v[220:221], v219 offset1:16
	ds_read2_b32 v[222:223], v219 offset0:32 offset1:48
	v_readlane_b32 s76, v247, 14
	v_readlane_b32 s77, v247, 15
	v_readlane_b32 s78, v247, 16
	v_readlane_b32 s79, v247, 17
	v_mov_b64_e32 v[68:69], s[76:77]
	s_waitcnt lgkmcnt(4)
	v_mfma_f32_16x16x32_bf16 v[64:67], v[206:209], v[210:213], 0
	v_mov_b64_e32 v[70:71], s[78:79]
	s_and_saveexec_b64 s[30:31], s[14:15]
	v_mfma_f32_16x16x32_bf16 v[68:71], v[210:213], v[206:209], 0
	s_or_b64 exec, exec, s[30:31]
	s_waitcnt lgkmcnt(2)
	v_mfma_f32_16x16x32_bf16 v[64:67], v[214:217], v[90:93], v[64:67]
	s_and_saveexec_b64 s[30:31], s[14:15]
	v_mfma_f32_16x16x32_bf16 v[68:71], v[90:93], v[214:217], v[68:71]
	s_or_b64 exec, exec, s[30:31]
	v_lshl_add_u32 v91, v96, 2, v95
	s_waitcnt lgkmcnt(0)
	v_add_f32_e32 v179, v220, v221
	v_add_f32_e32 v90, v222, v223
	v_add_f32_e32 v90, v179, v90
	v_max_f32_e32 v90, 0x179abe15, v90
	v_rsq_f32_e32 v90, v90
	s_and_saveexec_b64 s[30:31], s[16:17]
	ds_write_b32 v91, v90 offset:17664
	s_or_b64 exec, exec, s[30:31]
	ds_bpermute_b32 v91, v138, v90
	ds_bpermute_b32 v92, v139, v90
	v_cndmask_b32_e64 v93, 1.0, v90, s[6:7]
	ds_bpermute_b32 v179, v140, v90
	ds_bpermute_b32 v224, v141, v90
	s_waitcnt lgkmcnt(3)
	v_cndmask_b32_e64 v91, 1.0, v91, s[18:19]
	s_waitcnt lgkmcnt(2)
	v_cndmask_b32_e64 v92, 1.0, v92, s[18:19]
	v_mul_f32_e32 v91, v93, v91
	v_mul_f32_e32 v180, v98, v91
	v_mul_f32_e32 v92, v93, v92
	v_mul_f32_e32 v64, v64, v180
	v_mul_f32_e32 v180, v101, v92
	v_mul_f32_e32 v65, v65, v180
	s_waitcnt lgkmcnt(1)
	v_cndmask_b32_e64 v90, 1.0, v179, s[18:19]
	v_mul_f32_e32 v90, v93, v90
	v_mul_f32_e32 v179, v104, v90
	v_mul_f32_e32 v66, v66, v179
	s_waitcnt lgkmcnt(0)
	v_cndmask_b32_e64 v179, 1.0, v224, s[18:19]
	v_mul_f32_e32 v93, v93, v179
	v_mul_f32_e32 v179, v107, v93
	v_mul_f32_e32 v67, v67, v179
	s_and_saveexec_b64 s[30:31], s[14:15]
	s_cbranch_execz .LBB0_2759
	v_mul_f32_e32 v91, v99, v91
	v_mul_f32_e32 v90, v105, v90
	v_mul_f32_e32 v68, v68, v91
	v_mul_f32_e32 v91, v102, v92
	v_mul_f32_e32 v70, v70, v90
	v_mul_f32_e32 v90, v108, v93
	v_mul_f32_e32 v69, v69, v91
	v_mul_f32_e32 v71, v71, v90
	v_cvt_pk_bf16_f32 v90, v68, v69
	v_cvt_pk_bf16_f32 v91, v70, v71
	v_cvt_pk_bf16_f32 v92, v64, v65
	v_cvt_pk_bf16_f32 v93, v66, v67
	v_add_f32_e32 v64, v100, v64
	v_add_f32_e32 v65, v103, v65
	v_mfma_f32_16x16x16_bf16 v[68:71], v[92:93], v[90:91], 0
	v_add_f32_e32 v66, v106, v66
	v_add_f32_e32 v67, v109, v67
	v_mfma_f32_16x16x16_bf16 v[90:93], v[90:91], v[92:93], 0
	s_nop 4
	v_cvt_pk_bf16_f32 v180, v68, v69
	v_cvt_pk_bf16_f32 v181, v70, v71
	s_nop 0
	v_cvt_pk_bf16_f32 v90, v90, v91
	v_cvt_pk_bf16_f32 v91, v92, v93
	s_nop 1
	v_mfma_f32_16x16x16_bf16 v[68:71], v[90:91], v[180:181], 0
	v_mfma_f32_16x16x16_bf16 v[90:93], v[180:181], v[90:91], 0
	s_nop 6
	v_cvt_pk_bf16_f32 v194, v68, v69
	v_cvt_pk_bf16_f32 v195, v70, v71
	v_cvt_pk_bf16_f32 v68, v90, v91
	v_cvt_pk_bf16_f32 v69, v92, v93
	s_nop 1
	v_mfma_f32_16x16x16_bf16 v[68:71], v[68:69], v[194:195], 0
	s_nop 7
	v_cvt_pk_bf16_f32 v68, v68, v69
	v_cvt_pk_bf16_f32 v69, v70, v71
	v_cvt_pk_bf16_f32 v70, v64, v65
	v_cvt_pk_bf16_f32 v71, v66, v67
	s_nop 1
	v_mfma_f32_16x16x16_bf16 v[64:67], v[180:181], v[70:71], v[64:67]
	s_nop 7
	v_cvt_pk_bf16_f32 v70, v64, v65
	v_cvt_pk_bf16_f32 v71, v66, v67
	s_nop 1
	v_mfma_f32_16x16x16_bf16 v[64:67], v[194:195], v[70:71], v[64:67]
	s_nop 7
	v_cvt_pk_bf16_f32 v70, v64, v65
	v_cvt_pk_bf16_f32 v71, v66, v67
	s_nop 1
	v_mfma_f32_16x16x16_bf16 v[64:67], v[68:69], v[70:71], v[64:67]
